# P5 epilogue pipelined + P7 K-loop LDS-DMA issue split 3/5 between the SP1/SP2 load segments (As[b][0] piece 1 staged one segment later)
# speedup vs baseline: 1.0056x; 1.0056x over previous
; #define PG8_STAGE(bufoff, gbase, voff) do { _Pragma("unroll") for (int _i = 0; _i < 2; ++_i) \
;         __builtin_amdgcn_global_load_lds((const unsigned*)((const char*)(gbase) + (voff)[_i]), (PG8_LAS unsigned*)(lds + (bufoff) + ldsw + _i * 8192), 16, 0, 0); } while (0)
; #define PG8_WAIT_V(n) asm volatile("s_waitcnt vmcnt(" #n ")" ::: "memory")
; #define PG8_BAR __builtin_amdgcn_s_barrier()
; template <class Epi, class Sched, bool ALIGN_EPI = false, bool SP2 = false>
; __device__ __forceinline__ void gemm_phase(PG8_LAS unsigned char* lds, const Gemm g, const Sched& S, const Epi& E) {
;     ...
;     const unsigned ldsw = (unsigned)wid * 1024u;
;     const int aoff = lds_byte(wr * 64 + fr, fq * 8), boff = lds_byte(wc * 32 + fr, fq * 8);
;     ...
;         PG8_STAGE(PG8_SB(1, 0), cB + kstep, voffB); PG8_STAGE(PG8_SA(1, 0), cA + kstep, voffA); PG8_STAGE(PG8_SB(1, 1), cB + hstepB + kstep, voffB);
;         PG8_WAIT_V(6); PG8_BAR;
.LBB0_1101:
	s_add_u32 s8, s4, 0xb400000
	s_addc_u32 s9, s5, 0
	s_lshl_b32 s4, s10, 5
	s_mov_b64 s[10:11], 0x80
	s_and_b32 s24, s4, 0x60
	s_add_i32 m0, s31, 0x18000
	v_lshl_add_u64 v[6:7], v[6:7], 0, s[10:11]
	s_lshl_b32 s23, s22, 13
	s_lshl_b32 s25, s24, 7
	s_waitcnt vmcnt(2)
	s_barrier
	global_load_lds_dwordx4 v[6:7], off
	v_lshl_add_u64 v[4:5], v[4:5], 0, s[10:11]
	s_add_i32 m0, s31, 0x1a000
	s_add_i32 s55, s31, 0x8000
	s_add_i32 s56, s31, 0xa000
	global_load_lds_dwordx4 v[4:5], off
	v_lshl_add_u64 v[0:1], v[0:1], 0, s[10:11]
	s_mov_b32 m0, s55
	s_add_u32 s4, s36, 0x80080
	global_load_lds_dwordx4 v[0:1], off
	s_addc_u32 s5, s37, 0
	s_add_i32 m0, s31, 0x1c000
	v_lshl_add_u64 v[0:1], s[4:5], 0, v[132:133]
	global_load_lds_dwordx4 v[0:1], off
	v_lshl_add_u64 v[0:1], s[4:5], 0, v[128:129]
	s_add_i32 m0, s31, 0x1e000
	s_cmpk_lt_u32 s21, 0x100
	global_load_lds_dwordx4 v[0:1], off
	v_lshrrev_b32_e32 v1, 1, v8
	v_and_b32_e32 v1, 24, v1
	v_and_b32_e32 v0, 15, v8
	v_lshlrev_b32_e32 v2, 1, v1
	v_lshl_or_b32 v144, s22, 6, v0
	v_lshl_or_b32 v0, v0, 6, v2
	v_lshlrev_b32_e32 v2, 2, v8
	v_and_b32_e32 v2, 32, v2
	v_bitop3_b32 v3, v0, s23, v2 bitop3:0xde
	v_bitop3_b32 v145, v0, s25, v2 bitop3:0xde
	v_lshlrev_b32_e32 v0, 15, v13
	v_and_b32_e32 v0, 0xffff0000, v0
	v_or_b32_e32 v146, s24, v1
	v_lshl_add_u32 v0, v12, 12, v0
	v_and_b32_e32 v1, 1, v13
	v_lshl_or_b32 v0, v1, 6, v0
	v_lshl_add_u32 v136, v14, 1, v0
	v_lshlrev_b32_e32 v0, 15, v9
	v_and_b32_e32 v0, 0xffff0000, v0
	s_waitcnt vmcnt(5)
	v_lshl_add_u32 v0, v10, 12, v0
	v_and_b32_e32 v1, 1, v9
	s_sext_i32_i16 s33, s20
	s_cselect_b64 s[20:21], -1, 0
	v_lshl_or_b32 v0, v1, 6, v0
	s_add_i32 s59, 0, 0x10000
	s_add_i32 s60, 0, 0x14000
	s_ashr_i32 s57, s48, 31
	s_mov_b32 s58, s48
	v_mov_b32_e32 v137, v133
	v_lshl_add_u32 v138, v11, 1, v0
	v_mov_b32_e32 v139, v133
	v_mov_b64_e32 v[140:141], 0xbb0
	v_mov_b64_e32 v[142:143], 0xbaf
	v_add_u32_e32 v147, s59, v145
	v_add_u32_e32 v148, s60, v145
	v_add_u32_e32 v149, 0, v3
	s_movk_i32 s61, 0x2c00
	s_barrier
	s_branch .LBB0_1104

; #define PG8_STAGE(bufoff, gbase, voff) do { _Pragma("unroll") for (int _i = 0; _i < 2; ++_i) \
;         __builtin_amdgcn_global_load_lds((const unsigned*)((const char*)(gbase) + (voff)[_i]), (PG8_LAS unsigned*)(lds + (bufoff) + ldsw + _i * 8192), 16, 0, 0); } while (0)
; #define PG8_LDA(dst, b, h) do { _Pragma("unroll") for (int m = 0; m < 4; ++m) _Pragma("unroll") for (int k = 0; k < 2; ++k) dst[m][k] = *(const PG8_LAS bf16x8*)(lds + PG8_SA(b, h) + aoff + m * 2048 + k * 1024); } while (0)
; #define PG8_LDB(dst, b, h) do { _Pragma("unroll") for (int n = 0; n < 2; ++n) _Pragma("unroll") for (int k = 0; k < 2; ++k) dst[n][k] = *(const PG8_LAS bf16x8*)(lds + PG8_SB(b, h) + boff + n * 2048 + k * 1024); } while (0)
; #define PG8_MMA(ai, bj, At, Bt) do { __builtin_amdgcn_s_setprio(1); _Pragma("unroll") for (int m = 0; m < 4; ++m) _Pragma("unroll") for (int n = 0; n < 2; ++n) _Pragma("unroll") for (int k = 0; k < 2; ++k) \
;         acc[ai][bj][m][n] = __builtin_amdgcn_mfma_f32_16x16x32_bf16(Bt[n][k], At[m][k], acc[ai][bj][m][n], 0, 0, 0); __builtin_amdgcn_s_setprio(0); } while (0)
; #define PG8_WAIT_V(n) asm volatile("s_waitcnt vmcnt(" #n ")" ::: "memory")
; #define PG8_WAIT_L(n) asm volatile("s_waitcnt lgkmcnt(" #n ")" ::: "memory")
; #define PG8_BAR __builtin_amdgcn_s_barrier()
; #define PG8_SCHED __builtin_amdgcn_sched_barrier(0)
; template <class Epi, class Sched, bool ALIGN_EPI = false, bool SP2 = false>
; __device__ __forceinline__ void gemm_phase(PG8_LAS unsigned char* lds, const Gemm g, const Sched& S, const Epi& E) {
;     ...
;             PG8_LDB(B0, 0, 0); PG8_LDB(B1, 0, 1); PG8_SCHED; PG8_LDA(At, 0, 0); PG8_STAGE(PG8_SA(1, 1), a1 + hstepA, voffA);
;             PG8_WAIT_V(8); PG8_WAIT_L(0); PG8_BAR; PG8_MMA(0, 0, At, B0); PG8_MMA(0, 1, At, B1); PG8_BAR; PG8_SCHED;
;             PG8_LDA(At, 0, 1); PG8_STAGE(PG8_SB(0, 0), b2, voffB); PG8_STAGE(PG8_SB(0, 1), b2 + hstepB, voffB); PG8_STAGE(PG8_SA(0, 0), a2, voffA);
.LBB0_1108:
	ds_read_b128 v[150:153], v147
	ds_read_b128 v[154:157], v147 offset:1024
	ds_read_b128 v[158:161], v147 offset:2048
	ds_read_b128 v[162:165], v147 offset:3072
	ds_read_b128 v[166:169], v148
	ds_read_b128 v[170:173], v148 offset:1024
	ds_read_b128 v[174:177], v148 offset:2048
	ds_read_b128 v[178:181], v148 offset:3072
	s_add_u32 s98, s34, 0xfff80000
	s_addc_u32 s99, s35, -1
	s_add_i32 s68, s36, 2
	s_add_u32 s37, s34, 0xfff80080
	s_addc_u32 s38, s35, -1
	s_cmp_eq_u32 s65, s36
	s_cselect_b32 s36, s64, s66
	s_cselect_b32 s39, s25, s38
	s_cselect_b32 s38, s62, s37
	s_cselect_b32 s37, s63, s67
	v_lshl_add_u64 v[222:223], s[98:99], 0, v[130:131]
	s_mov_b32 m0, s56
	ds_read_b128 v[182:185], v149
	ds_read_b128 v[186:189], v149 offset:1024
	ds_read_b128 v[190:193], v149 offset:2048
	ds_read_b128 v[194:197], v149 offset:3072
	ds_read_b128 v[198:201], v149 offset:4096
	ds_read_b128 v[202:205], v149 offset:5120
	ds_read_b128 v[208:211], v149 offset:6144
	ds_read_b128 v[212:215], v149 offset:7168
	global_load_lds_dwordx4 v[222:223], off
	v_lshl_add_u64 v[206:207], s[34:35], 0, v[136:137]
	s_add_i32 m0, s31, 0xc000
	s_nop 0
	global_load_lds_dwordx4 v[206:207], off
	v_lshl_add_u64 v[206:207], s[34:35], 0, v[138:139]
	s_add_i32 m0, s31, 0xe000
	s_nop 0
	global_load_lds_dwordx4 v[206:207], off
	s_waitcnt vmcnt(8)
	s_waitcnt lgkmcnt(0)
	s_barrier
	s_setprio 1
	s_waitcnt lgkmcnt(0)
	v_mfma_f32_16x16x32_bf16 v[124:127], v[150:153], v[182:185], v[124:127]
	v_mfma_f32_16x16x32_bf16 v[116:119], v[158:161], v[182:185], v[116:119]
	v_mfma_f32_16x16x32_bf16 v[108:111], v[150:153], v[190:193], v[108:111]
	v_mfma_f32_16x16x32_bf16 v[100:103], v[158:161], v[190:193], v[100:103]
	v_mfma_f32_16x16x32_bf16 v[92:95], v[150:153], v[198:201], v[92:95]
	v_mfma_f32_16x16x32_bf16 v[84:87], v[158:161], v[198:201], v[84:87]
	v_mfma_f32_16x16x32_bf16 v[76:79], v[150:153], v[208:211], v[76:79]
	v_mfma_f32_16x16x32_bf16 v[68:71], v[158:161], v[208:211], v[68:71]
	v_mfma_f32_16x16x32_bf16 v[124:127], v[154:157], v[186:189], v[124:127]
	v_mfma_f32_16x16x32_bf16 v[116:119], v[162:165], v[186:189], v[116:119]
	v_mfma_f32_16x16x32_bf16 v[108:111], v[154:157], v[194:197], v[108:111]
	v_mfma_f32_16x16x32_bf16 v[100:103], v[162:165], v[194:197], v[100:103]
	v_mfma_f32_16x16x32_bf16 v[92:95], v[154:157], v[202:205], v[92:95]
	v_mfma_f32_16x16x32_bf16 v[84:87], v[162:165], v[202:205], v[84:87]
	v_mfma_f32_16x16x32_bf16 v[76:79], v[154:157], v[212:215], v[76:79]
	v_mfma_f32_16x16x32_bf16 v[68:71], v[162:165], v[212:215], v[68:71]
	s_setprio 0
	s_setprio 1
	v_mfma_f32_16x16x32_bf16 v[120:123], v[166:169], v[182:185], v[120:123]
	v_mfma_f32_16x16x32_bf16 v[112:115], v[174:177], v[182:185], v[112:115]
	v_mfma_f32_16x16x32_bf16 v[104:107], v[166:169], v[190:193], v[104:107]
	v_mfma_f32_16x16x32_bf16 v[96:99], v[174:177], v[190:193], v[96:99]
	v_mfma_f32_16x16x32_bf16 v[88:91], v[166:169], v[198:201], v[88:91]
	v_mfma_f32_16x16x32_bf16 v[80:83], v[174:177], v[198:201], v[80:83]
	v_mfma_f32_16x16x32_bf16 v[72:75], v[166:169], v[208:211], v[72:75]
	v_mfma_f32_16x16x32_bf16 v[64:67], v[174:177], v[208:211], v[64:67]
	v_mfma_f32_16x16x32_bf16 v[120:123], v[170:173], v[186:189], v[120:123]
	v_mfma_f32_16x16x32_bf16 v[112:115], v[178:181], v[186:189], v[112:115]
	v_mfma_f32_16x16x32_bf16 v[104:107], v[170:173], v[194:197], v[104:107]
	v_mfma_f32_16x16x32_bf16 v[96:99], v[178:181], v[194:197], v[96:99]
	v_mfma_f32_16x16x32_bf16 v[88:91], v[170:173], v[202:205], v[88:91]
	v_mfma_f32_16x16x32_bf16 v[80:83], v[178:181], v[202:205], v[80:83]
	v_mfma_f32_16x16x32_bf16 v[72:75], v[170:173], v[212:215], v[72:75]
	v_mfma_f32_16x16x32_bf16 v[64:67], v[178:181], v[212:215], v[64:67]
	s_setprio 0
	s_barrier
	s_add_i32 s69, s59, s45
	v_lshl_add_u64 v[206:207], s[36:37], 0, v[132:133]
	s_mov_b32 m0, s69
	ds_read_b128 v[182:185], v149 offset:16384
	ds_read_b128 v[186:189], v149 offset:17408
	ds_read_b128 v[190:193], v149 offset:18432
	ds_read_b128 v[194:197], v149 offset:19456
	ds_read_b128 v[198:201], v149 offset:20480
	ds_read_b128 v[202:205], v149 offset:21504
	ds_read_b128 v[208:211], v149 offset:22528
	ds_read_b128 v[212:215], v149 offset:23552
	global_load_lds_dwordx4 v[206:207], off
	s_add_i32 m0, s69, 0x2000
	s_add_u32 s70, s36, 0x80000
	v_lshl_add_u64 v[216:217], s[36:37], 0, v[128:129]
	s_addc_u32 s71, s37, 0
	s_add_i32 s69, s60, s45
	global_load_lds_dwordx4 v[216:217], off
	v_lshl_add_u64 v[218:219], s[70:71], 0, v[132:133]
	s_mov_b32 m0, s69
	v_lshl_add_u64 v[220:221], s[38:39], 0, v[130:131]
	global_load_lds_dwordx4 v[218:219], off
	v_lshl_add_u64 v[218:219], s[70:71], 0, v[128:129]
	s_add_i32 m0, s69, 0x2000
	s_nop 0
	global_load_lds_dwordx4 v[218:219], off
	v_lshl_add_u64 v[218:219], s[38:39], 0, v[134:135]
	s_mov_b32 m0, s31
	s_nop 0
	global_load_lds_dwordx4 v[218:219], off
	s_waitcnt vmcnt(7)
	s_waitcnt lgkmcnt(0)
	s_barrier
; #define PG8_STAGE(bufoff, gbase, voff) do { _Pragma("unroll") for (int _i = 0; _i < 2; ++_i) \
;         __builtin_amdgcn_global_load_lds((const unsigned*)((const char*)(gbase) + (voff)[_i]), (PG8_LAS unsigned*)(lds + (bufoff) + ldsw + _i * 8192), 16, 0, 0); } while (0)
; #define PG8_LDA(dst, b, h) do { _Pragma("unroll") for (int m = 0; m < 4; ++m) _Pragma("unroll") for (int k = 0; k < 2; ++k) dst[m][k] = *(const PG8_LAS bf16x8*)(lds + PG8_SA(b, h) + aoff + m * 2048 + k * 1024); } while (0)
; #define PG8_LDB(dst, b, h) do { _Pragma("unroll") for (int n = 0; n < 2; ++n) _Pragma("unroll") for (int k = 0; k < 2; ++k) dst[n][k] = *(const PG8_LAS bf16x8*)(lds + PG8_SB(b, h) + boff + n * 2048 + k * 1024); } while (0)
; #define PG8_MMA(ai, bj, At, Bt) do { __builtin_amdgcn_s_setprio(1); _Pragma("unroll") for (int m = 0; m < 4; ++m) _Pragma("unroll") for (int n = 0; n < 2; ++n) _Pragma("unroll") for (int k = 0; k < 2; ++k) \
;         acc[ai][bj][m][n] = __builtin_amdgcn_mfma_f32_16x16x32_bf16(Bt[n][k], At[m][k], acc[ai][bj][m][n], 0, 0, 0); __builtin_amdgcn_s_setprio(0); } while (0)
; #define PG8_WAIT_V(n) asm volatile("s_waitcnt vmcnt(" #n ")" ::: "memory")
; #define PG8_WAIT_L(n) asm volatile("s_waitcnt lgkmcnt(" #n ")" ::: "memory")
; #define PG8_BAR __builtin_amdgcn_s_barrier()
; #define PG8_SCHED __builtin_amdgcn_sched_barrier(0)
; template <class Epi, class Sched, bool ALIGN_EPI = false, bool SP2 = false>
; __device__ __forceinline__ void gemm_phase(PG8_LAS unsigned char* lds, const Gemm g, const Sched& S, const Epi& E) {
;     ...
;             PG8_WAIT_V(8); PG8_WAIT_L(0); PG8_BAR; PG8_MMA(1, 0, At, B0); PG8_MMA(1, 1, At, B1); PG8_BAR; PG8_SCHED;
;             PG8_LDB(B0, 1, 0); PG8_LDB(B1, 1, 1); PG8_SCHED; PG8_LDA(At, 1, 0); PG8_STAGE(PG8_SA(0, 1), a2 + hstepA, voffA);
;             PG8_WAIT_V(8); PG8_WAIT_L(0); PG8_BAR; PG8_MMA(0, 0, At, B0); PG8_MMA(0, 1, At, B1); PG8_BAR; PG8_SCHED;
	s_setprio 1
	s_waitcnt lgkmcnt(0)
	v_mfma_f32_16x16x32_bf16 v[60:63], v[150:153], v[182:185], v[60:63]
	v_mfma_f32_16x16x32_bf16 v[52:55], v[158:161], v[182:185], v[52:55]
	v_mfma_f32_16x16x32_bf16 v[44:47], v[150:153], v[190:193], v[44:47]
	v_mfma_f32_16x16x32_bf16 v[36:39], v[158:161], v[190:193], v[36:39]
	v_mfma_f32_16x16x32_bf16 v[28:31], v[150:153], v[198:201], v[28:31]
	v_mfma_f32_16x16x32_bf16 v[20:23], v[158:161], v[198:201], v[20:23]
	v_mfma_f32_16x16x32_bf16 v[12:15], v[150:153], v[208:211], v[12:15]
	v_mfma_f32_16x16x32_bf16 v[4:7], v[158:161], v[208:211], v[4:7]
	v_mfma_f32_16x16x32_bf16 v[60:63], v[154:157], v[186:189], v[60:63]
	v_mfma_f32_16x16x32_bf16 v[52:55], v[162:165], v[186:189], v[52:55]
	v_mfma_f32_16x16x32_bf16 v[44:47], v[154:157], v[194:197], v[44:47]
	v_mfma_f32_16x16x32_bf16 v[36:39], v[162:165], v[194:197], v[36:39]
	v_mfma_f32_16x16x32_bf16 v[28:31], v[154:157], v[202:205], v[28:31]
	v_mfma_f32_16x16x32_bf16 v[20:23], v[162:165], v[202:205], v[20:23]
	v_mfma_f32_16x16x32_bf16 v[12:15], v[154:157], v[212:215], v[12:15]
	v_mfma_f32_16x16x32_bf16 v[4:7], v[162:165], v[212:215], v[4:7]
	s_setprio 0
	s_setprio 1
	v_mfma_f32_16x16x32_bf16 v[56:59], v[166:169], v[182:185], v[56:59]
	v_mfma_f32_16x16x32_bf16 v[48:51], v[174:177], v[182:185], v[48:51]
	v_mfma_f32_16x16x32_bf16 v[40:43], v[166:169], v[190:193], v[40:43]
	v_mfma_f32_16x16x32_bf16 v[32:35], v[174:177], v[190:193], v[32:35]
	v_mfma_f32_16x16x32_bf16 v[24:27], v[166:169], v[198:201], v[24:27]
	v_mfma_f32_16x16x32_bf16 v[16:19], v[174:177], v[198:201], v[16:19]
	v_mfma_f32_16x16x32_bf16 v[8:11], v[166:169], v[208:211], v[8:11]
	v_mfma_f32_16x16x32_bf16 v[0:3], v[174:177], v[208:211], v[0:3]
	v_mfma_f32_16x16x32_bf16 v[56:59], v[170:173], v[186:189], v[56:59]
	v_mfma_f32_16x16x32_bf16 v[48:51], v[178:181], v[186:189], v[48:51]
	v_mfma_f32_16x16x32_bf16 v[40:43], v[170:173], v[194:197], v[40:43]
	v_mfma_f32_16x16x32_bf16 v[32:35], v[178:181], v[194:197], v[32:35]
	v_mfma_f32_16x16x32_bf16 v[24:27], v[170:173], v[202:205], v[24:27]
	v_mfma_f32_16x16x32_bf16 v[16:19], v[178:181], v[202:205], v[16:19]
	v_mfma_f32_16x16x32_bf16 v[8:11], v[170:173], v[212:215], v[8:11]
	v_mfma_f32_16x16x32_bf16 v[0:3], v[178:181], v[212:215], v[0:3]
	s_setprio 0
	s_barrier
	s_add_i32 s69, 0, 0x18000
	s_add_i32 s70, 0, 0x1c000
	v_add_u32_e32 v162, s69, v145
	v_add_u32_e32 v178, s70, v145
	ds_read_b128 v[150:153], v162
	ds_read_b128 v[154:157], v162 offset:1024
	ds_read_b128 v[158:161], v162 offset:2048
	ds_read_b128 v[162:165], v162 offset:3072
	ds_read_b128 v[166:169], v178
	ds_read_b128 v[170:173], v178 offset:1024
	ds_read_b128 v[174:177], v178 offset:2048
	ds_read_b128 v[178:181], v178 offset:3072
	s_add_u32 s38, s38, 0x80000
	s_addc_u32 s39, s39, 0
	s_mov_b32 m0, s51
	v_lshl_add_u64 v[222:223], s[38:39], 0, v[134:135]
	ds_read_b128 v[182:185], v149 offset:32768
	ds_read_b128 v[186:189], v149 offset:33792
	ds_read_b128 v[190:193], v149 offset:34816
	ds_read_b128 v[194:197], v149 offset:35840
	ds_read_b128 v[198:201], v149 offset:36864
	ds_read_b128 v[202:205], v149 offset:37888
	ds_read_b128 v[208:211], v149 offset:38912
	ds_read_b128 v[212:215], v149 offset:39936
	global_load_lds_dwordx4 v[220:221], off
	s_mov_b32 m0, s52
	s_nop 0
	global_load_lds_dwordx4 v[222:223], off
	v_lshl_add_u64 v[222:223], s[38:39], 0, v[130:131]
	s_mov_b32 m0, s53
	s_nop 0
	global_load_lds_dwordx4 v[222:223], off
	s_waitcnt vmcnt(8)
	s_waitcnt lgkmcnt(0)
	s_barrier
	s_setprio 1
	s_waitcnt lgkmcnt(0)
	v_mfma_f32_16x16x32_bf16 v[124:127], v[150:153], v[182:185], v[124:127]
	v_mfma_f32_16x16x32_bf16 v[116:119], v[158:161], v[182:185], v[116:119]
	v_mfma_f32_16x16x32_bf16 v[108:111], v[150:153], v[190:193], v[108:111]
	v_mfma_f32_16x16x32_bf16 v[100:103], v[158:161], v[190:193], v[100:103]
	v_mfma_f32_16x16x32_bf16 v[92:95], v[150:153], v[198:201], v[92:95]
	v_mfma_f32_16x16x32_bf16 v[84:87], v[158:161], v[198:201], v[84:87]
	v_mfma_f32_16x16x32_bf16 v[76:79], v[150:153], v[208:211], v[76:79]
	v_mfma_f32_16x16x32_bf16 v[68:71], v[158:161], v[208:211], v[68:71]
	v_mfma_f32_16x16x32_bf16 v[124:127], v[154:157], v[186:189], v[124:127]
	v_mfma_f32_16x16x32_bf16 v[116:119], v[162:165], v[186:189], v[116:119]
	v_mfma_f32_16x16x32_bf16 v[108:111], v[154:157], v[194:197], v[108:111]
	v_mfma_f32_16x16x32_bf16 v[100:103], v[162:165], v[194:197], v[100:103]
	v_mfma_f32_16x16x32_bf16 v[92:95], v[154:157], v[202:205], v[92:95]
	v_mfma_f32_16x16x32_bf16 v[84:87], v[162:165], v[202:205], v[84:87]
	v_mfma_f32_16x16x32_bf16 v[76:79], v[154:157], v[212:215], v[76:79]
	v_mfma_f32_16x16x32_bf16 v[68:71], v[162:165], v[212:215], v[68:71]
	s_setprio 0
	s_setprio 1
	v_mfma_f32_16x16x32_bf16 v[120:123], v[166:169], v[182:185], v[120:123]
	v_mfma_f32_16x16x32_bf16 v[112:115], v[174:177], v[182:185], v[112:115]
	v_mfma_f32_16x16x32_bf16 v[104:107], v[166:169], v[190:193], v[104:107]
	v_mfma_f32_16x16x32_bf16 v[96:99], v[174:177], v[190:193], v[96:99]
	v_mfma_f32_16x16x32_bf16 v[88:91], v[166:169], v[198:201], v[88:91]
	v_mfma_f32_16x16x32_bf16 v[80:83], v[174:177], v[198:201], v[80:83]
	v_mfma_f32_16x16x32_bf16 v[72:75], v[166:169], v[208:211], v[72:75]
	v_mfma_f32_16x16x32_bf16 v[64:67], v[174:177], v[208:211], v[64:67]
	v_mfma_f32_16x16x32_bf16 v[120:123], v[170:173], v[186:189], v[120:123]
	v_mfma_f32_16x16x32_bf16 v[112:115], v[178:181], v[186:189], v[112:115]
	v_mfma_f32_16x16x32_bf16 v[104:107], v[170:173], v[194:197], v[104:107]
	v_mfma_f32_16x16x32_bf16 v[96:99], v[178:181], v[194:197], v[96:99]
	v_mfma_f32_16x16x32_bf16 v[88:91], v[170:173], v[202:205], v[88:91]
	v_mfma_f32_16x16x32_bf16 v[80:83], v[178:181], v[202:205], v[80:83]
	v_mfma_f32_16x16x32_bf16 v[72:75], v[170:173], v[212:215], v[72:75]
	v_mfma_f32_16x16x32_bf16 v[64:67], v[178:181], v[212:215], v[64:67]
	s_setprio 0
	s_barrier
; #define PG8_STAGE(bufoff, gbase, voff) do { _Pragma("unroll") for (int _i = 0; _i < 2; ++_i) \
;         __builtin_amdgcn_global_load_lds((const unsigned*)((const char*)(gbase) + (voff)[_i]), (PG8_LAS unsigned*)(lds + (bufoff) + ldsw + _i * 8192), 16, 0, 0); } while (0)
; #define PG8_LDA(dst, b, h) do { _Pragma("unroll") for (int m = 0; m < 4; ++m) _Pragma("unroll") for (int k = 0; k < 2; ++k) dst[m][k] = *(const PG8_LAS bf16x8*)(lds + PG8_SA(b, h) + aoff + m * 2048 + k * 1024); } while (0)
; #define PG8_MMA(ai, bj, At, Bt) do { __builtin_amdgcn_s_setprio(1); _Pragma("unroll") for (int m = 0; m < 4; ++m) _Pragma("unroll") for (int n = 0; n < 2; ++n) _Pragma("unroll") for (int k = 0; k < 2; ++k) \
;         acc[ai][bj][m][n] = __builtin_amdgcn_mfma_f32_16x16x32_bf16(Bt[n][k], At[m][k], acc[ai][bj][m][n], 0, 0, 0); __builtin_amdgcn_s_setprio(0); } while (0)
; #define PG8_WAIT_V(n) asm volatile("s_waitcnt vmcnt(" #n ")" ::: "memory")
; #define PG8_WAIT_L(n) asm volatile("s_waitcnt lgkmcnt(" #n ")" ::: "memory")
; #define PG8_BAR __builtin_amdgcn_s_barrier()
; #define PG8_SCHED __builtin_amdgcn_sched_barrier(0)
; template <class Epi, class Sched, bool ALIGN_EPI = false, bool SP2 = false>
; __device__ __forceinline__ void gemm_phase(PG8_LAS unsigned char* lds, const Gemm g, const Sched& S, const Epi& E) {
;     ...
;         for (int t = 0; t < nt; t += 2) {
;             const bool last = (t == nt - 2);
;             const char* a1 = cA + (size_t)(t + 1) * kstep;
;             const char* a2 = last ? nA : cA + (size_t)(t + 2) * kstep; const char* b2 = last ? nB : cB + (size_t)(t + 2) * kstep;
;             const char* a3 = a2 + kstep; const char* b3 = b2 + kstep;
;     ...
;             PG8_WAIT_V(8); PG8_WAIT_L(0); PG8_BAR; PG8_MMA(0, 0, At, B0); PG8_MMA(0, 1, At, B1); PG8_BAR; PG8_SCHED;
;             PG8_LDA(At, 1, 1); PG8_STAGE(PG8_SB(1, 0), b3, voffB); PG8_STAGE(PG8_SB(1, 1), b3 + hstepB, voffB); PG8_STAGE(PG8_SA(1, 0), a3, voffA);
;             PG8_WAIT_V(8); PG8_WAIT_L(0); PG8_BAR; PG8_MMA(1, 0, At, B0); PG8_MMA(1, 1, At, B1); PG8_BAR; PG8_SCHED;
	s_add_i32 s38, s69, s45
	v_lshl_add_u64 v[206:207], v[206:207], 0, s[10:11]
	s_mov_b32 m0, s38
	ds_read_b128 v[182:185], v149 offset:49152
	ds_read_b128 v[186:189], v149 offset:50176
	ds_read_b128 v[190:193], v149 offset:51200
	ds_read_b128 v[194:197], v149 offset:52224
	ds_read_b128 v[198:201], v149 offset:53248
	ds_read_b128 v[202:205], v149 offset:54272
	ds_read_b128 v[208:211], v149 offset:55296
	ds_read_b128 v[212:215], v149 offset:56320
	global_load_lds_dwordx4 v[206:207], off
	s_add_i32 m0, s38, 0x2000
	s_add_u32 s36, s36, 0x80080
	v_lshl_add_u64 v[206:207], v[216:217], 0, s[10:11]
	s_addc_u32 s37, s37, 0
	s_add_i32 s38, s70, s45
	global_load_lds_dwordx4 v[206:207], off
	v_lshl_add_u64 v[206:207], s[36:37], 0, v[132:133]
	s_mov_b32 m0, s38
	s_nop 0
	global_load_lds_dwordx4 v[206:207], off
	v_lshl_add_u64 v[206:207], s[36:37], 0, v[128:129]
	s_add_i32 m0, s38, 0x2000
	s_nop 0
	global_load_lds_dwordx4 v[206:207], off
	v_lshl_add_u64 v[206:207], v[218:219], 0, s[10:11]
	s_mov_b32 m0, s55
	s_nop 0
	global_load_lds_dwordx4 v[206:207], off
	s_waitcnt vmcnt(7)
	s_waitcnt lgkmcnt(0)
	s_barrier
	s_setprio 1
	s_waitcnt lgkmcnt(0)
	v_mfma_f32_16x16x32_bf16 v[60:63], v[150:153], v[182:185], v[60:63]
	v_mfma_f32_16x16x32_bf16 v[52:55], v[158:161], v[182:185], v[52:55]
	v_mfma_f32_16x16x32_bf16 v[44:47], v[150:153], v[190:193], v[44:47]
	v_mfma_f32_16x16x32_bf16 v[36:39], v[158:161], v[190:193], v[36:39]
	v_mfma_f32_16x16x32_bf16 v[28:31], v[150:153], v[198:201], v[28:31]
	v_mfma_f32_16x16x32_bf16 v[20:23], v[158:161], v[198:201], v[20:23]
	v_mfma_f32_16x16x32_bf16 v[12:15], v[150:153], v[208:211], v[12:15]
	v_mfma_f32_16x16x32_bf16 v[4:7], v[158:161], v[208:211], v[4:7]
	v_mfma_f32_16x16x32_bf16 v[60:63], v[154:157], v[186:189], v[60:63]
	v_mfma_f32_16x16x32_bf16 v[52:55], v[162:165], v[186:189], v[52:55]
	v_mfma_f32_16x16x32_bf16 v[44:47], v[154:157], v[194:197], v[44:47]
	v_mfma_f32_16x16x32_bf16 v[36:39], v[162:165], v[194:197], v[36:39]
	v_mfma_f32_16x16x32_bf16 v[28:31], v[154:157], v[202:205], v[28:31]
	v_mfma_f32_16x16x32_bf16 v[20:23], v[162:165], v[202:205], v[20:23]
	v_mfma_f32_16x16x32_bf16 v[12:15], v[154:157], v[212:215], v[12:15]
	v_mfma_f32_16x16x32_bf16 v[4:7], v[162:165], v[212:215], v[4:7]
	s_setprio 0
	s_setprio 1
	v_mfma_f32_16x16x32_bf16 v[56:59], v[166:169], v[182:185], v[56:59]
	v_mfma_f32_16x16x32_bf16 v[48:51], v[174:177], v[182:185], v[48:51]
	v_mfma_f32_16x16x32_bf16 v[40:43], v[166:169], v[190:193], v[40:43]
	v_mfma_f32_16x16x32_bf16 v[32:35], v[174:177], v[190:193], v[32:35]
	v_mfma_f32_16x16x32_bf16 v[24:27], v[166:169], v[198:201], v[24:27]
	v_mfma_f32_16x16x32_bf16 v[16:19], v[174:177], v[198:201], v[16:19]
	v_mfma_f32_16x16x32_bf16 v[8:11], v[166:169], v[208:211], v[8:11]
	v_mfma_f32_16x16x32_bf16 v[0:3], v[174:177], v[208:211], v[0:3]
	v_mfma_f32_16x16x32_bf16 v[56:59], v[170:173], v[186:189], v[56:59]
	v_mfma_f32_16x16x32_bf16 v[48:51], v[178:181], v[186:189], v[48:51]
	v_mfma_f32_16x16x32_bf16 v[40:43], v[170:173], v[194:197], v[40:43]
	v_mfma_f32_16x16x32_bf16 v[32:35], v[178:181], v[194:197], v[32:35]
	v_mfma_f32_16x16x32_bf16 v[24:27], v[170:173], v[202:205], v[24:27]
	v_mfma_f32_16x16x32_bf16 v[16:19], v[178:181], v[202:205], v[16:19]
	v_mfma_f32_16x16x32_bf16 v[8:11], v[170:173], v[212:215], v[8:11]
	v_mfma_f32_16x16x32_bf16 v[0:3], v[178:181], v[212:215], v[0:3]
	s_setprio 0
	s_barrier
	s_add_u32 s34, s34, 0x100
	s_addc_u32 s35, s35, 0
	s_add_u32 s66, s66, 0x100
	s_addc_u32 s67, s67, 0
	s_cmp_ge_i32 s68, s23
	s_mov_b32 s36, s68
	s_cbranch_scc0 .LBB0_1108
	s_and_b64 vcc, exec, s[20:21]
	s_cbranch_vccz .LBB0_1111
